# opt25: opt19 + diff-attention loop: tile sa+2's four LDS-DMA pieces moved from the loop head to after QK(b) (saddr form, offsets carried in s90/s91)
# speedup vs baseline: 1.0138x; 1.0138x over previous
; #define DMA_T(s_) do { DMA_K(s_); DMA_V(s_); } while (0)
; #define CLASSIFY(kv0_, act_, cls_) do { act_ = true; if (SWA) act_ = ((kv0_) + 63 >= qw - 128) && ((kv0_) <= qw + 159); \
;         cls_ = 0; if ((kv0_) + 63 < qw) cls_ = 1; else if ((kv0_) > qw + 31) cls_ = 2; \
;         if (SWA) { if (cls_ == 1 && qw + 31 - (kv0_) > 128) cls_ = 0; if (cls_ == 2 && (kv0_) + 63 - qw > 128) cls_ = 0; } } while (0)
; template <bool SWA>
; __device__ __forceinline__ void unit(LAS unsigned char* lds, const bf16_t* PROJ, const bf16_t* KT, const bf16_t* VT, bf16_t* OB, int opitch, int ocol, int b, int head, int qb, float slope2, float m_init, float lam, const float* subg) {
;     ...
;     for (int S = 0; S < npairs; ++S) {
;         const int sa = 2 * S, sb = 2 * S + 1;
;         if (sa + 2 < nsteps) DMA_T(sa + 2);
;         if (sb + 2 < nsteps) DMA_T(sb + 2);
;         const int kva = TILE_OF(sa) * 64, kvb = TILE_OF(sb < nsteps ? sb : sa) * 64;
;         bool acta, actb; int clsa, clsb;
;         CLASSIFY(kva, acta, clsa); CLASSIFY(kvb, actb, clsb); actb = actb && (sb < nsteps);
;         f32x16 s0, s1, u0, u1;
;         if (acta) QK_T(s0, s1, sa, clsa);
.LBB0_884:
	s_add_i32 s29, s1, -3
	s_add_i32 s27, s1, -2
	s_add_i32 s6, s1, -1
	s_cmp_lt_u32 s29, s0
	s_cselect_b32 s6, s29, s6
	s_mov_b32 s28, s26
	s_lshl_b32 s26, s6, 14
	s_mov_b32 s90, s26
	s_add_i32 s30, s25, 0xffffc000
	s_and_b32 s91, s30, 0x8000
	s_cmp_lt_u32 s27, s0
	s_cselect_b32 s6, s27, s1
	s_lshl_b32 s26, s6, 14
	s_add_u32 s98, s73, s26
	s_addc_u32 s99, s17, 0
	s_add_u32 s100, s2, s26
	s_addc_u32 s101, s23, 0
	s_and_b32 s30, s25, 0xc000
	s_add_i32 s32, s30, s33
	s_add_i32 s71, s30, s72
	s_add_i32 s26, s28, 0x80
	s_cmp_gt_u32 s29, s0
	s_cselect_b64 s[78:79], -1, 0
	s_and_b64 s[6:7], s[78:79], exec
	s_cselect_b32 s30, s26, s28
	s_or_b32 s28, s30, 63
	s_cmp_ge_i32 s28, s5
	s_cselect_b64 s[6:7], -1, 0
	s_cmp_lt_i32 s28, s5
	s_cselect_b64 s[82:83], -1, 0
	s_cmp_le_i32 s30, s19
	s_cselect_b64 s[80:81], -1, 0
	s_and_b64 s[84:85], s[6:7], s[80:81]
	s_and_b64 vcc, exec, s[84:85]
	v_mov_b32_e32 v64, 0
	s_cbranch_vccnz .LBB0_886
	s_and_b64 s[28:29], s[80:81], exec
	s_cselect_b32 s28, 0, 64
	s_and_b64 s[6:7], s[6:7], exec
	s_cselect_b32 s6, s28, 0
	s_add_i32 s6, s6, 0
	s_add_i32 s6, s6, 0x20200
	v_mov_b32_e32 v65, s6
	ds_read_b128 v[96:99], v65
	ds_read_b128 v[100:103], v65 offset:16
	ds_read_b128 v[104:107], v65 offset:32
	ds_read_b128 v[108:111], v65 offset:48
	s_branch .LBB0_887

.LBB0_889:
	s_add_i32 s6, s25, 0xffff8000
	s_and_b32 s6, s6, 0xc000
	s_add_i32 s27, s6, 0
	v_add_u32_e32 v80, s27, v199
	ds_read_b128 v[204:207], v80
	ds_read_b128 v[208:211], v80 offset:8192
	v_add_u32_e32 v80, s27, v200
	ds_read_b128 v[212:215], v80
	ds_read_b128 v[216:219], v80 offset:8192
	v_add_u32_e32 v80, s27, v201
	ds_read_b128 v[220:223], v80
	ds_read_b128 v[224:227], v80 offset:8192
	v_add_u32_e32 v80, s27, v202
	ds_read_b128 v[228:231], v80
	ds_read_b128 v[232:235], v80 offset:8192
	s_xor_b64 s[34:35], s[84:85], -1
	s_setprio 1
	s_waitcnt lgkmcnt(7)
	v_mfma_f32_32x32x16_bf16 v[80:95], v[204:207], v[140:143], v[64:79]
	s_waitcnt lgkmcnt(6)
	v_mfma_f32_32x32x16_bf16 v[64:79], v[208:211], v[140:143], v[64:79]
	s_waitcnt lgkmcnt(5)
	v_mfma_f32_32x32x16_bf16 v[80:95], v[212:215], v[136:139], v[80:95]
	s_waitcnt lgkmcnt(4)
	v_mfma_f32_32x32x16_bf16 v[64:79], v[216:219], v[136:139], v[64:79]
	s_waitcnt lgkmcnt(3)
	v_mfma_f32_32x32x16_bf16 v[80:95], v[220:223], v[132:135], v[80:95]
	s_waitcnt lgkmcnt(2)
	v_mfma_f32_32x32x16_bf16 v[64:79], v[224:227], v[132:135], v[64:79]
	s_waitcnt lgkmcnt(1)
	v_mfma_f32_32x32x16_bf16 v[80:95], v[228:231], v[128:131], v[80:95]
	s_waitcnt lgkmcnt(0)
	v_mfma_f32_32x32x16_bf16 v[64:79], v[232:235], v[128:131], v[64:79]
	s_setprio 0
	s_mov_b32 m0, s71
	s_nop 0
	global_load_lds_dwordx4 v168, s[100:101]
	s_add_i32 m0, s71, 0x400
	s_nop 0
	global_load_lds_dwordx4 v172, s[100:101]
	s_add_u32 s98, s73, s90
	s_addc_u32 s99, s17, 0
	s_add_i32 s92, s91, s33
	s_mov_b32 m0, s92
	s_nop 0
	global_load_lds_dwordx4 v164, s[98:99]
	s_add_i32 m0, s92, 0x400
	s_nop 0
	global_load_lds_dwordx4 v170, s[98:99]
	s_add_u32 s98, s2, s90
	s_addc_u32 s99, s23, 0
	s_add_i32 s92, s91, s72
	s_mov_b32 m0, s92
	s_nop 0
	global_load_lds_dwordx4 v168, s[98:99]
	s_add_i32 m0, s92, 0x400
	s_nop 0
	global_load_lds_dwordx4 v172, s[98:99]
	v_or_b32_e32 v174, s30, v187
	v_sub_u32_e32 v174, v188, v174
	v_cvt_f32_i32_e32 v174, v174
	s_mov_b64 s[6:7], -1
	s_and_b64 vcc, exec, s[34:35]
	s_cbranch_vccz .LBB0_895
	s_andn2_b64 vcc, exec, s[82:83]
	s_cbranch_vccnz .LBB0_892
	v_mul_f32_e64 v204, -s76, v174
	v_fma_f32 v205, -s76, v174, v194
	s_mov_b64 s[6:7], 0
